# stack with hand-written two-level barrier at sites 1-5 (constant epochs, early invalidate) instead of bar_nowb
# speedup vs baseline: 1.0272x; 1.0148x over previous
.LBB0_220:
	s_cmp_gt_i32 s83, 2
	s_cselect_b64 s[0:1], -1, 0
	s_and_b64 s[4:5], s[28:29], s[0:1]
	s_andn2_b64 vcc, exec, s[4:5]
	s_cbranch_vccnz .LBB0_274
	s_waitcnt vmcnt(0)
	s_waitcnt vmcnt(0)
	s_barrier
	s_and_saveexec_b64 s[4:5], s[94:95]
	s_cbranch_execz .LBB0_273
	v_mov_b32_e32 v1, 0x23ff0
	ds_read_b32 v2, v1
	ds_read_b32 v3, v1 offset:4
	s_add_u32 s6, s80, 0x2380000
	s_addc_u32 s7, s81, 0
	s_lshl_b32 s8, s87, 8
	s_add_i32 s9, s8, 0x1400
	s_add_i32 s8, s8, 0x2400
	v_mov_b32_e32 v4, s9
	v_mov_b32_e32 v5, 1
	global_atomic_add v6, v4, v5, s[6:7] sc0
	buffer_inv sc1
	s_waitcnt vmcnt(0) lgkmcnt(0)
	v_readfirstlane_b32 s10, v6
	v_readfirstlane_b32 s11, v2
	v_readfirstlane_b32 s16, v3
	s_add_i32 s10, s10, 1
	s_mul_i32 s11, s11, 2
	s_cmp_lg_u32 s10, s11
	s_cbranch_scc1 .Lxb_nl_1
	buffer_wbl2 sc1
	s_waitcnt vmcnt(0)
	v_mov_b32_e32 v4, 0x3400
	global_atomic_add v6, v4, v5, s[6:7] sc0
	s_waitcnt vmcnt(0)
	v_readfirstlane_b32 s10, v6
	s_add_i32 s10, s10, 1
	s_mul_i32 s16, s16, 2
	v_mov_b32_e32 v4, 0x3500
	s_cmp_lg_u32 s10, s16
	s_cbranch_scc1 .Lxb_tw_1
	global_atomic_add v4, v5, s[6:7]
	s_branch .Lxb_rel_1
.Lxb_tw_1:
	s_mov_b32 s10, 0
.Lxb_tw2_1:
	s_sleep 1
	global_load_dword v6, v4, s[6:7] sc1
	s_waitcnt vmcnt(0)
	v_readfirstlane_b32 s11, v6
	s_cmp_ge_u32 s11, 2
	s_cbranch_scc1 .Lxb_rel_1
	s_add_i32 s10, s10, 1
	s_cmp_lt_u32 s10, 0x100000
	s_cbranch_scc1 .Lxb_tw2_1
.Lxb_rel_1:
	v_mov_b32_e32 v4, s8
	global_atomic_add v4, v5, s[6:7]
	s_branch .Lxb_done_1
.Lxb_nl_1:
	v_mov_b32_e32 v4, s8
	s_mov_b32 s10, 0
.Lxb_nl2_1:
	global_load_dword v6, v4, s[6:7] sc1
	s_waitcnt vmcnt(0)
	v_readfirstlane_b32 s11, v6
	s_cmp_ge_u32 s11, 2
	s_cbranch_scc1 .Lxb_done_1
	s_sleep 1
	s_add_i32 s10, s10, 1
	s_cmp_lt_u32 s10, 0x100000
	s_cbranch_scc1 .Lxb_nl2_1
.Lxb_done_1:
	s_waitcnt vmcnt(0)
.LBB0_273:
	s_or_b64 exec, exec, s[4:5]
	s_waitcnt lgkmcnt(0)
	s_barrier

.LBB0_349:
	s_cmp_gt_i32 s83, 3
	s_cselect_b64 s[0:1], -1, 0
	s_and_b64 s[4:5], s[18:19], s[0:1]
	s_andn2_b64 vcc, exec, s[4:5]
	s_cbranch_vccnz .LBB0_403
	s_waitcnt vmcnt(0)
	s_waitcnt vmcnt(0)
	s_barrier
	s_and_saveexec_b64 s[4:5], s[94:95]
	s_cbranch_execz .LBB0_402
	v_mov_b32_e32 v1, 0x23ff0
	ds_read_b32 v2, v1
	ds_read_b32 v3, v1 offset:4
	s_add_u32 s6, s80, 0x2380000
	s_addc_u32 s7, s81, 0
	s_lshl_b32 s8, s87, 8
	s_add_i32 s9, s8, 0x1400
	s_add_i32 s8, s8, 0x2400
	v_mov_b32_e32 v4, s9
	v_mov_b32_e32 v5, 1
	global_atomic_add v6, v4, v5, s[6:7] sc0
	buffer_inv sc1
	s_waitcnt vmcnt(0) lgkmcnt(0)
	v_readfirstlane_b32 s10, v6
	v_readfirstlane_b32 s11, v2
	v_readfirstlane_b32 s16, v3
	s_add_i32 s10, s10, 1
	s_mul_i32 s11, s11, 3
	s_cmp_lg_u32 s10, s11
	s_cbranch_scc1 .Lxb_nl_2
	buffer_wbl2 sc1
	s_waitcnt vmcnt(0)
	v_mov_b32_e32 v4, 0x3400
	global_atomic_add v6, v4, v5, s[6:7] sc0
	s_waitcnt vmcnt(0)
	v_readfirstlane_b32 s10, v6
	s_add_i32 s10, s10, 1
	s_mul_i32 s16, s16, 3
	v_mov_b32_e32 v4, 0x3500
	s_cmp_lg_u32 s10, s16
	s_cbranch_scc1 .Lxb_tw_2
	global_atomic_add v4, v5, s[6:7]
	s_branch .Lxb_rel_2

.Lxb_tw2_2:
	s_sleep 1
	global_load_dword v6, v4, s[6:7] sc1
	s_waitcnt vmcnt(0)
	v_readfirstlane_b32 s11, v6
	s_cmp_ge_u32 s11, 3
	s_cbranch_scc1 .Lxb_rel_2
	s_add_i32 s10, s10, 1
	s_cmp_lt_u32 s10, 0x100000
	s_cbranch_scc1 .Lxb_tw2_2

.Lxb_nl2_2:
	global_load_dword v6, v4, s[6:7] sc1
	s_waitcnt vmcnt(0)
	v_readfirstlane_b32 s11, v6
	s_cmp_ge_u32 s11, 3
	s_cbranch_scc1 .Lxb_done_2
	s_sleep 1
	s_add_i32 s10, s10, 1
	s_cmp_lt_u32 s10, 0x100000
	s_cbranch_scc1 .Lxb_nl2_2
.Lxb_done_2:
	s_waitcnt vmcnt(0)
.LBB0_402:
	s_or_b64 exec, exec, s[4:5]
	s_waitcnt lgkmcnt(0)
	s_barrier

.LBB0_434:
	s_cmp_gt_i32 s83, 4
	s_cselect_b64 s[0:1], -1, 0
	s_and_b64 s[4:5], s[6:7], s[0:1]
	s_andn2_b64 vcc, exec, s[4:5]
	s_cbranch_vccnz .LBB0_488
	s_waitcnt vmcnt(0)
	s_waitcnt vmcnt(0)
	s_barrier
	s_and_saveexec_b64 s[4:5], s[94:95]
	s_cbranch_execz .LBB0_487
	v_mov_b32_e32 v1, 0x23ff0
	ds_read_b32 v2, v1
	ds_read_b32 v3, v1 offset:4
	s_add_u32 s6, s80, 0x2380000
	s_addc_u32 s7, s81, 0
	s_lshl_b32 s8, s87, 8
	s_add_i32 s9, s8, 0x1400
	s_add_i32 s8, s8, 0x2400
	v_mov_b32_e32 v4, s9
	v_mov_b32_e32 v5, 1
	global_atomic_add v6, v4, v5, s[6:7] sc0
	buffer_inv sc1
	s_waitcnt vmcnt(0) lgkmcnt(0)
	v_readfirstlane_b32 s10, v6
	v_readfirstlane_b32 s11, v2
	v_readfirstlane_b32 s16, v3
	s_add_i32 s10, s10, 1
	s_mul_i32 s11, s11, 4
	s_cmp_lg_u32 s10, s11
	s_cbranch_scc1 .Lxb_nl_3
	v_mov_b32_e32 v4, 0x3400
	global_atomic_add v6, v4, v5, s[6:7] sc0
	s_waitcnt vmcnt(0)
	v_readfirstlane_b32 s10, v6
	s_add_i32 s10, s10, 1
	s_mul_i32 s16, s16, 4
	v_mov_b32_e32 v4, 0x3500
	s_cmp_lg_u32 s10, s16
	s_cbranch_scc1 .Lxb_tw_3
	global_atomic_add v4, v5, s[6:7]
	s_branch .Lxb_rel_3

.Lxb_tw2_3:
	s_sleep 1
	global_load_dword v6, v4, s[6:7] sc1
	s_waitcnt vmcnt(0)
	v_readfirstlane_b32 s11, v6
	s_cmp_ge_u32 s11, 4
	s_cbranch_scc1 .Lxb_rel_3
	s_add_i32 s10, s10, 1
	s_cmp_lt_u32 s10, 0x100000
	s_cbranch_scc1 .Lxb_tw2_3

.Lxb_nl2_3:
	global_load_dword v6, v4, s[6:7] sc1
	s_waitcnt vmcnt(0)
	v_readfirstlane_b32 s11, v6
	s_cmp_ge_u32 s11, 4
	s_cbranch_scc1 .Lxb_done_3
	s_sleep 1
	s_add_i32 s10, s10, 1
	s_cmp_lt_u32 s10, 0x100000
	s_cbranch_scc1 .Lxb_nl2_3
.Lxb_done_3:
	s_waitcnt vmcnt(0)
.LBB0_487:
	s_or_b64 exec, exec, s[4:5]
	s_waitcnt lgkmcnt(0)
	s_barrier

.LBB0_529:
	s_cmp_gt_i32 s83, 5
	s_cselect_b64 s[0:1], -1, 0
	s_and_b64 s[4:5], s[16:17], s[0:1]
	s_andn2_b64 vcc, exec, s[4:5]
	s_cbranch_vccnz .LBB0_583
	s_waitcnt vmcnt(0)
	s_waitcnt vmcnt(0) lgkmcnt(0)
	s_barrier
	s_and_saveexec_b64 s[4:5], s[94:95]
	s_cbranch_execz .LBB0_582
	v_mov_b32_e32 v1, 0x23ff0
	ds_read_b32 v2, v1
	ds_read_b32 v3, v1 offset:4
	s_add_u32 s6, s80, 0x2380000
	s_addc_u32 s7, s81, 0
	s_lshl_b32 s8, s87, 8
	s_add_i32 s9, s8, 0x1400
	s_add_i32 s8, s8, 0x2400
	v_mov_b32_e32 v4, s9
	v_mov_b32_e32 v5, 1
	global_atomic_add v6, v4, v5, s[6:7] sc0
	buffer_inv sc1
	s_waitcnt vmcnt(0) lgkmcnt(0)
	v_readfirstlane_b32 s10, v6
	v_readfirstlane_b32 s11, v2
	v_readfirstlane_b32 s16, v3
	s_add_i32 s10, s10, 1
	s_mul_i32 s11, s11, 5
	s_cmp_lg_u32 s10, s11
	s_cbranch_scc1 .Lxb_nl_4
	v_mov_b32_e32 v4, 0x3400
	global_atomic_add v6, v4, v5, s[6:7] sc0
	s_waitcnt vmcnt(0)
	v_readfirstlane_b32 s10, v6
	s_add_i32 s10, s10, 1
	s_mul_i32 s16, s16, 5
	v_mov_b32_e32 v4, 0x3500
	s_cmp_lg_u32 s10, s16
	s_cbranch_scc1 .Lxb_tw_4
	global_atomic_add v4, v5, s[6:7]
	s_branch .Lxb_rel_4

.Lxb_tw2_4:
	s_sleep 1
	global_load_dword v6, v4, s[6:7] sc1
	s_waitcnt vmcnt(0)
	v_readfirstlane_b32 s11, v6
	s_cmp_ge_u32 s11, 5
	s_cbranch_scc1 .Lxb_rel_4
	s_add_i32 s10, s10, 1
	s_cmp_lt_u32 s10, 0x100000
	s_cbranch_scc1 .Lxb_tw2_4

.Lxb_nl2_4:
	global_load_dword v6, v4, s[6:7] sc1
	s_waitcnt vmcnt(0)
	v_readfirstlane_b32 s11, v6
	s_cmp_ge_u32 s11, 5
	s_cbranch_scc1 .Lxb_done_4
	s_sleep 1
	s_add_i32 s10, s10, 1
	s_cmp_lt_u32 s10, 0x100000
	s_cbranch_scc1 .Lxb_nl2_4
.Lxb_done_4:
	s_waitcnt vmcnt(0)
.LBB0_582:
	s_or_b64 exec, exec, s[4:5]
	s_waitcnt lgkmcnt(0)
	s_barrier

.LBB0_612:
	s_cmp_gt_i32 s83, 6
	s_cselect_b64 s[0:1], -1, 0
	s_and_b64 s[4:5], s[6:7], s[0:1]
	s_andn2_b64 vcc, exec, s[4:5]
	s_cbranch_vccnz .LBB0_666
	s_waitcnt vmcnt(0)
	s_waitcnt vmcnt(0) lgkmcnt(0)
	s_barrier
	s_and_saveexec_b64 s[4:5], s[94:95]
	s_cbranch_execz .LBB0_665
	v_mov_b32_e32 v1, 0x23ff0
	ds_read_b32 v2, v1
	ds_read_b32 v3, v1 offset:4
	s_add_u32 s6, s80, 0x2380000
	s_addc_u32 s7, s81, 0
	s_lshl_b32 s8, s87, 8
	s_add_i32 s9, s8, 0x1400
	s_add_i32 s8, s8, 0x2400
	v_mov_b32_e32 v4, s9
	v_mov_b32_e32 v5, 1
	global_atomic_add v6, v4, v5, s[6:7] sc0
	buffer_inv sc1
	s_waitcnt vmcnt(0) lgkmcnt(0)
	v_readfirstlane_b32 s10, v6
	v_readfirstlane_b32 s11, v2
	v_readfirstlane_b32 s16, v3
	s_add_i32 s10, s10, 1
	s_mul_i32 s11, s11, 6
	s_cmp_lg_u32 s10, s11
	s_cbranch_scc1 .Lxb_nl_5
	v_mov_b32_e32 v4, 0x3400
	global_atomic_add v6, v4, v5, s[6:7] sc0
	s_waitcnt vmcnt(0)
	v_readfirstlane_b32 s10, v6
	s_add_i32 s10, s10, 1
	s_mul_i32 s16, s16, 6
	v_mov_b32_e32 v4, 0x3500
	s_cmp_lg_u32 s10, s16
	s_cbranch_scc1 .Lxb_tw_5
	global_atomic_add v4, v5, s[6:7]
	s_branch .Lxb_rel_5

.Lxb_tw2_5:
	s_sleep 1
	global_load_dword v6, v4, s[6:7] sc1
	s_waitcnt vmcnt(0)
	v_readfirstlane_b32 s11, v6
	s_cmp_ge_u32 s11, 6
	s_cbranch_scc1 .Lxb_rel_5
	s_add_i32 s10, s10, 1
	s_cmp_lt_u32 s10, 0x100000
	s_cbranch_scc1 .Lxb_tw2_5

.Lxb_nl2_5:
	global_load_dword v6, v4, s[6:7] sc1
	s_waitcnt vmcnt(0)
	v_readfirstlane_b32 s11, v6
	s_cmp_ge_u32 s11, 6
	s_cbranch_scc1 .Lxb_done_5
	s_sleep 1
	s_add_i32 s10, s10, 1
	s_cmp_lt_u32 s10, 0x100000
	s_cbranch_scc1 .Lxb_nl2_5
.Lxb_done_5:
	s_waitcnt vmcnt(0)
.LBB0_665:
	s_or_b64 exec, exec, s[4:5]
	s_waitcnt lgkmcnt(0)
	s_barrier
